# memory cross-attention through LDS: leading/trailing wave halves (waves 4-7 one barrier behind) so that on every SIMD one wave reads LDS while the other issues its MFMAs
# baseline (speedup 1.0000x reference)
; __device__ __forceinline__ f32x4 mfma16(bf16x8 a, bf16x8 b, f32x4 c) { return __builtin_amdgcn_mfma_f32_16x16x32_bf16(a, b, c, 0, 0, 0); }
; __device__ __forceinline__ void mem_task(bf16_t* zb, const bf16_t* kvm_b, const bf16_t* vmt_b, int hm, int t0, int lane, bool do_store) {
;     const int n = lane & 15, fq = lane >> 4;
;     bf16_t* qp = zb + (size_t)(t0 + n) * ZM + ZC_QM + hm * 256;
;     bf16x8 qf[8];
; #pragma unroll
;     for (int kk = 0; kk < 8; ++kk) qf[kk] = *(const bf16x8*)(qp + kk * 32 + 8 * fq);
;     f32x4 zero4 = {0.f, 0.f, 0.f, 0.f}; asm volatile("" : "+v"(zero4));
;     f32x4 s[16];
;     const bf16_t* kbase = kvm_b + (size_t)(8 * (n >> 2) + (n & 3)) * 2048 + hm * 256 + 8 * fq;
;     bf16x8 kfr[3][8];
; #pragma unroll
;     for (int kk = 0; kk < 8; ++kk) kfr[0][kk] = *(const bf16x8*)(kbase + kk * 32);
;     { const bf16_t* kp = kbase + (size_t)4 * 2048;
; #pragma unroll
;       for (int kk = 0; kk < 8; ++kk) kfr[1][kk] = *(const bf16x8*)(kp + kk * 32); }
; #pragma unroll
;     for (int kt = 0; kt < 16; ++kt) {
;         if (kt + 2 < 16) { const bf16_t* kp = kbase + (size_t)(((kt + 2) >> 1) * 32 + 4 * ((kt + 2) & 1)) * 2048;
; #pragma unroll
;             for (int kk = 0; kk < 8; ++kk) kfr[(kt + 2) % 3][kk] = *(const bf16x8*)(kp + kk * 32); }
;         f32x4 acc = zero4;
;         __builtin_amdgcn_s_setprio(1);
; #pragma unroll
;         for (int kk = 0; kk < 8; ++kk) acc = mfma16(kfr[kt % 3][kk], qf[kk], acc);
;         __builtin_amdgcn_s_setprio(0);
;         s[kt] = acc; }
.LBB0_366:
	v_and_or_b32 v186, s0, -16, v65
	v_mov_b64_e32 v[188:189], s[78:79]
	s_and_b32 s2, s3, 0x300
	v_mad_i64_i32 v[188:189], s[6:7], v186, s11, v[188:189]
	s_lshl_b32 s38, s2, 1
	v_lshl_add_u64 v[188:189], v[188:189], 0, s[38:39]
	v_lshl_add_u64 v[184:185], v[188:189], 0, s[16:17]
	v_mov_b32_e32 v143, v64
	v_mov_b32_e32 v145, v64
	v_lshl_add_u64 v[188:189], v[184:185], 0, v[142:143]
	global_load_dwordx4 v[0:3], v[188:189], off
	global_load_dwordx4 v[4:7], v[188:189], off offset:64
	global_load_dwordx4 v[8:11], v[188:189], off offset:128
	global_load_dwordx4 v[12:15], v[188:189], off offset:192
	global_load_dwordx4 v[16:19], v[188:189], off offset:256
	global_load_dwordx4 v[20:23], v[188:189], off offset:320
	global_load_dwordx4 v[24:27], v[188:189], off offset:384
	global_load_dwordx4 v[28:31], v[188:189], off offset:448
	v_lshl_add_u64 v[184:185], v[184:185], 0, v[144:145]
	s_lshl_b32 s98, s2, 9
	s_mov_b32 s99, 0
	v_lshl_add_u64 v[180:181], v[66:67], 0, s[98:99]
	v_lshl_add_u64 v[182:183], v[140:141], 0, s[98:99]
	s_lshl_b32 s7, s89, 10
	s_sub_u32 s98, s7, 0x1000
	s_subb_u32 s99, 0, 0
	v_lshl_add_u64 v[180:181], v[180:181], 0, s[98:99]
	v_lshl_add_u64 v[182:183], v[182:183], 0, s[98:99]
	v_lshlrev_b32_e32 v178, 4, v204
	v_add_u32_e32 v179, 0x10000, v178
	s_mov_b64 s[98:99], 0x2000
	s_add_i32 m0, s7, 0
	s_nop 0
	global_load_lds_dwordx4 v[180:181], off
	v_lshl_add_u64 v[180:181], v[180:181], 0, s[98:99]
	s_add_i32 m0, s7, 8192
	s_nop 0
	global_load_lds_dwordx4 v[180:181], off
	v_lshl_add_u64 v[180:181], v[180:181], 0, s[98:99]
	s_add_i32 m0, s7, 16384
	s_nop 0
	global_load_lds_dwordx4 v[180:181], off
	v_lshl_add_u64 v[180:181], v[180:181], 0, s[98:99]
	s_add_i32 m0, s7, 24576
	s_nop 0
	global_load_lds_dwordx4 v[180:181], off
	v_lshl_add_u64 v[180:181], v[180:181], 0, s[98:99]
	s_add_i32 m0, s7, 32768
	s_nop 0
	global_load_lds_dwordx4 v[180:181], off
	v_lshl_add_u64 v[180:181], v[180:181], 0, s[98:99]
	s_add_i32 m0, s7, 40960
	s_nop 0
	global_load_lds_dwordx4 v[180:181], off
	v_lshl_add_u64 v[180:181], v[180:181], 0, s[98:99]
	s_add_i32 m0, s7, 49152
	s_nop 0
	global_load_lds_dwordx4 v[180:181], off
	v_lshl_add_u64 v[180:181], v[180:181], 0, s[98:99]
	s_add_i32 m0, s7, 57344
	s_nop 0
	global_load_lds_dwordx4 v[180:181], off
	v_lshl_add_u64 v[180:181], v[180:181], 0, s[98:99]
	s_add_i32 m0, s7, 65536
	s_nop 0
	global_load_lds_dwordx4 v[180:181], off
	v_lshl_add_u64 v[180:181], v[180:181], 0, s[98:99]
	s_add_i32 m0, s7, 73728
	s_nop 0
	global_load_lds_dwordx4 v[180:181], off
	v_lshl_add_u64 v[180:181], v[180:181], 0, s[98:99]
	s_add_i32 m0, s7, 81920
	s_nop 0
	global_load_lds_dwordx4 v[180:181], off
	v_lshl_add_u64 v[180:181], v[180:181], 0, s[98:99]
	s_add_i32 m0, s7, 90112
	s_nop 0
	global_load_lds_dwordx4 v[180:181], off
	v_lshl_add_u64 v[180:181], v[180:181], 0, s[98:99]
	s_waitcnt vmcnt(10)
	s_cmp_lt_u32 s89, 4
	s_cbranch_scc1 .Lmem_r_lead0
	s_barrier
.Lmem_r_lead0:
	s_barrier
	s_add_i32 m0, s7, 98304
	s_nop 0
	global_load_lds_dwordx4 v[180:181], off
	v_lshl_add_u64 v[180:181], v[180:181], 0, s[98:99]
	s_add_i32 m0, s7, 106496
	s_nop 0
	global_load_lds_dwordx4 v[180:181], off
	v_lshl_add_u64 v[180:181], v[180:181], 0, s[98:99]
	ds_read_b128 v[104:107], v178 offset:0
	ds_read_b128 v[146:149], v178 offset:8192
	ds_read_b128 v[108:111], v178 offset:1024
	ds_read_b128 v[150:153], v178 offset:9216
	ds_read_b128 v[112:115], v178 offset:2048
	ds_read_b128 v[154:157], v178 offset:10240
	ds_read_b128 v[116:119], v178 offset:3072
	ds_read_b128 v[158:161], v178 offset:11264
	ds_read_b128 v[120:123], v178 offset:4096
	ds_read_b128 v[162:165], v178 offset:12288
	ds_read_b128 v[124:127], v178 offset:5120
	ds_read_b128 v[166:169], v178 offset:13312
	ds_read_b128 v[128:131], v178 offset:6144
	ds_read_b128 v[170:173], v178 offset:14336
	ds_read_b128 v[132:135], v178 offset:7168
	ds_read_b128 v[174:177], v178 offset:15360
	s_waitcnt lgkmcnt(0)
	s_waitcnt vmcnt(10)
	s_barrier
	v_mfma_f32_16x16x32_bf16 v[32:35], v[104:107], v[0:3], 0
	v_mfma_f32_16x16x32_bf16 v[36:39], v[146:149], v[0:3], 0
	v_mfma_f32_16x16x32_bf16 v[32:35], v[108:111], v[4:7], v[32:35]
	v_mfma_f32_16x16x32_bf16 v[36:39], v[150:153], v[4:7], v[36:39]
	v_mfma_f32_16x16x32_bf16 v[32:35], v[112:115], v[8:11], v[32:35]
	v_mfma_f32_16x16x32_bf16 v[36:39], v[154:157], v[8:11], v[36:39]
	v_mfma_f32_16x16x32_bf16 v[32:35], v[116:119], v[12:15], v[32:35]
	v_mfma_f32_16x16x32_bf16 v[36:39], v[158:161], v[12:15], v[36:39]
	v_mfma_f32_16x16x32_bf16 v[32:35], v[120:123], v[16:19], v[32:35]
	v_mfma_f32_16x16x32_bf16 v[36:39], v[162:165], v[16:19], v[36:39]
	v_mfma_f32_16x16x32_bf16 v[32:35], v[124:127], v[20:23], v[32:35]
	v_mfma_f32_16x16x32_bf16 v[36:39], v[166:169], v[20:23], v[36:39]
	v_mfma_f32_16x16x32_bf16 v[32:35], v[128:131], v[24:27], v[32:35]
	v_mfma_f32_16x16x32_bf16 v[36:39], v[170:173], v[24:27], v[36:39]
	v_mfma_f32_16x16x32_bf16 v[32:35], v[132:135], v[28:31], v[32:35]
	v_mfma_f32_16x16x32_bf16 v[36:39], v[174:177], v[28:31], v[36:39]
	s_barrier
	s_add_i32 m0, s7, 114688
	s_nop 0
	global_load_lds_dwordx4 v[180:181], off
	v_lshl_add_u64 v[180:181], v[180:181], 0, s[98:99]
	s_add_i32 m0, s7, 122880
	s_nop 0
	global_load_lds_dwordx4 v[180:181], off
	v_lshl_add_u64 v[180:181], v[180:181], 0, s[98:99]
	ds_read_b128 v[104:107], v178 offset:16384
	ds_read_b128 v[146:149], v178 offset:24576
	ds_read_b128 v[108:111], v178 offset:17408
	ds_read_b128 v[150:153], v178 offset:25600
	ds_read_b128 v[112:115], v178 offset:18432
	ds_read_b128 v[154:157], v178 offset:26624
	ds_read_b128 v[116:119], v178 offset:19456
	ds_read_b128 v[158:161], v178 offset:27648
	ds_read_b128 v[120:123], v178 offset:20480
	ds_read_b128 v[162:165], v178 offset:28672
	ds_read_b128 v[124:127], v178 offset:21504
	ds_read_b128 v[166:169], v178 offset:29696
	ds_read_b128 v[128:131], v178 offset:22528
	ds_read_b128 v[170:173], v178 offset:30720
	ds_read_b128 v[132:135], v178 offset:23552
	ds_read_b128 v[174:177], v178 offset:31744
	s_waitcnt lgkmcnt(0)
	s_waitcnt vmcnt(10)
	s_barrier
; __device__ __forceinline__ f32x4 mfma16(bf16x8 a, bf16x8 b, f32x4 c) { return __builtin_amdgcn_mfma_f32_16x16x32_bf16(a, b, c, 0, 0, 0); }
; __device__ __forceinline__ void mem_task(bf16_t* zb, const bf16_t* kvm_b, const bf16_t* vmt_b, int hm, int t0, int lane, bool do_store) {
;     ...
;     for (int kt = 0; kt < 16; ++kt) {
;         if (kt + 2 < 16) { const bf16_t* kp = kbase + (size_t)(((kt + 2) >> 1) * 32 + 4 * ((kt + 2) & 1)) * 2048;
; #pragma unroll
;             for (int kk = 0; kk < 8; ++kk) kfr[(kt + 2) % 3][kk] = *(const bf16x8*)(kp + kk * 32); }
;         f32x4 acc = zero4;
;         __builtin_amdgcn_s_setprio(1);
; #pragma unroll
;         for (int kk = 0; kk < 8; ++kk) acc = mfma16(kfr[kt % 3][kk], qf[kk], acc);
;         __builtin_amdgcn_s_setprio(0);
;         s[kt] = acc; }
	v_mfma_f32_16x16x32_bf16 v[40:43], v[104:107], v[0:3], 0
	v_mfma_f32_16x16x32_bf16 v[44:47], v[146:149], v[0:3], 0
	v_mfma_f32_16x16x32_bf16 v[40:43], v[108:111], v[4:7], v[40:43]
	v_mfma_f32_16x16x32_bf16 v[44:47], v[150:153], v[4:7], v[44:47]
	v_mfma_f32_16x16x32_bf16 v[40:43], v[112:115], v[8:11], v[40:43]
	v_mfma_f32_16x16x32_bf16 v[44:47], v[154:157], v[8:11], v[44:47]
	v_mfma_f32_16x16x32_bf16 v[40:43], v[116:119], v[12:15], v[40:43]
	v_mfma_f32_16x16x32_bf16 v[44:47], v[158:161], v[12:15], v[44:47]
	v_mfma_f32_16x16x32_bf16 v[40:43], v[120:123], v[16:19], v[40:43]
	v_mfma_f32_16x16x32_bf16 v[44:47], v[162:165], v[16:19], v[44:47]
	v_mfma_f32_16x16x32_bf16 v[40:43], v[124:127], v[20:23], v[40:43]
	v_mfma_f32_16x16x32_bf16 v[44:47], v[166:169], v[20:23], v[44:47]
	v_mfma_f32_16x16x32_bf16 v[40:43], v[128:131], v[24:27], v[40:43]
	v_mfma_f32_16x16x32_bf16 v[44:47], v[170:173], v[24:27], v[44:47]
	v_mfma_f32_16x16x32_bf16 v[40:43], v[132:135], v[28:31], v[40:43]
	v_mfma_f32_16x16x32_bf16 v[44:47], v[174:177], v[28:31], v[44:47]
	s_barrier
	s_add_i32 m0, s7, 0
	s_nop 0
	global_load_lds_dwordx4 v[182:183], off
	v_lshl_add_u64 v[182:183], v[182:183], 0, s[98:99]
	s_add_i32 m0, s7, 8192
	s_nop 0
	global_load_lds_dwordx4 v[182:183], off
	v_lshl_add_u64 v[182:183], v[182:183], 0, s[98:99]
	ds_read_b128 v[104:107], v178 offset:32768
	ds_read_b128 v[146:149], v178 offset:40960
	ds_read_b128 v[108:111], v178 offset:33792
	ds_read_b128 v[150:153], v178 offset:41984
	ds_read_b128 v[112:115], v178 offset:34816
	ds_read_b128 v[154:157], v178 offset:43008
	ds_read_b128 v[116:119], v178 offset:35840
	ds_read_b128 v[158:161], v178 offset:44032
	ds_read_b128 v[120:123], v178 offset:36864
	ds_read_b128 v[162:165], v178 offset:45056
	ds_read_b128 v[124:127], v178 offset:37888
	ds_read_b128 v[166:169], v178 offset:46080
	ds_read_b128 v[128:131], v178 offset:38912
	ds_read_b128 v[170:173], v178 offset:47104
	ds_read_b128 v[132:135], v178 offset:39936
	ds_read_b128 v[174:177], v178 offset:48128
	s_waitcnt lgkmcnt(0)
	s_waitcnt vmcnt(10)
	s_barrier
	v_mfma_f32_16x16x32_bf16 v[48:51], v[104:107], v[0:3], 0
	v_mfma_f32_16x16x32_bf16 v[52:55], v[146:149], v[0:3], 0
	v_mfma_f32_16x16x32_bf16 v[48:51], v[108:111], v[4:7], v[48:51]
	v_mfma_f32_16x16x32_bf16 v[52:55], v[150:153], v[4:7], v[52:55]
	v_mfma_f32_16x16x32_bf16 v[48:51], v[112:115], v[8:11], v[48:51]
	v_mfma_f32_16x16x32_bf16 v[52:55], v[154:157], v[8:11], v[52:55]
	v_mfma_f32_16x16x32_bf16 v[48:51], v[116:119], v[12:15], v[48:51]
	v_mfma_f32_16x16x32_bf16 v[52:55], v[158:161], v[12:15], v[52:55]
	v_mfma_f32_16x16x32_bf16 v[48:51], v[120:123], v[16:19], v[48:51]
	v_mfma_f32_16x16x32_bf16 v[52:55], v[162:165], v[16:19], v[52:55]
	v_mfma_f32_16x16x32_bf16 v[48:51], v[124:127], v[20:23], v[48:51]
	v_mfma_f32_16x16x32_bf16 v[52:55], v[166:169], v[20:23], v[52:55]
	v_mfma_f32_16x16x32_bf16 v[48:51], v[128:131], v[24:27], v[48:51]
	v_mfma_f32_16x16x32_bf16 v[52:55], v[170:173], v[24:27], v[52:55]
	v_mfma_f32_16x16x32_bf16 v[48:51], v[132:135], v[28:31], v[48:51]
	v_mfma_f32_16x16x32_bf16 v[52:55], v[174:177], v[28:31], v[52:55]
	s_barrier
	s_add_i32 m0, s7, 16384
	s_nop 0
	global_load_lds_dwordx4 v[182:183], off
	v_lshl_add_u64 v[182:183], v[182:183], 0, s[98:99]
	s_add_i32 m0, s7, 24576
	s_nop 0
	global_load_lds_dwordx4 v[182:183], off
	v_lshl_add_u64 v[182:183], v[182:183], 0, s[98:99]
	ds_read_b128 v[104:107], v178 offset:49152
	ds_read_b128 v[146:149], v178 offset:57344
	ds_read_b128 v[108:111], v178 offset:50176
	ds_read_b128 v[150:153], v178 offset:58368
	ds_read_b128 v[112:115], v178 offset:51200
	ds_read_b128 v[154:157], v178 offset:59392
	ds_read_b128 v[116:119], v178 offset:52224
	ds_read_b128 v[158:161], v178 offset:60416
	ds_read_b128 v[120:123], v178 offset:53248
	ds_read_b128 v[162:165], v178 offset:61440
	ds_read_b128 v[124:127], v178 offset:54272
	ds_read_b128 v[166:169], v178 offset:62464
	ds_read_b128 v[128:131], v178 offset:55296
	ds_read_b128 v[170:173], v178 offset:63488
	ds_read_b128 v[132:135], v178 offset:56320
	ds_read_b128 v[174:177], v178 offset:64512
	s_waitcnt lgkmcnt(0)
	s_waitcnt vmcnt(10)
	s_barrier
	v_mfma_f32_16x16x32_bf16 v[56:59], v[104:107], v[0:3], 0
	v_mfma_f32_16x16x32_bf16 v[60:63], v[146:149], v[0:3], 0
	v_mfma_f32_16x16x32_bf16 v[56:59], v[108:111], v[4:7], v[56:59]
	v_mfma_f32_16x16x32_bf16 v[60:63], v[150:153], v[4:7], v[60:63]
	v_mfma_f32_16x16x32_bf16 v[56:59], v[112:115], v[8:11], v[56:59]
	v_mfma_f32_16x16x32_bf16 v[60:63], v[154:157], v[8:11], v[60:63]
	v_mfma_f32_16x16x32_bf16 v[56:59], v[116:119], v[12:15], v[56:59]
	v_mfma_f32_16x16x32_bf16 v[60:63], v[158:161], v[12:15], v[60:63]
	v_mfma_f32_16x16x32_bf16 v[56:59], v[120:123], v[16:19], v[56:59]
	v_mfma_f32_16x16x32_bf16 v[60:63], v[162:165], v[16:19], v[60:63]
	v_mfma_f32_16x16x32_bf16 v[56:59], v[124:127], v[20:23], v[56:59]
	v_mfma_f32_16x16x32_bf16 v[60:63], v[166:169], v[20:23], v[60:63]
	v_mfma_f32_16x16x32_bf16 v[56:59], v[128:131], v[24:27], v[56:59]
	v_mfma_f32_16x16x32_bf16 v[60:63], v[170:173], v[24:27], v[60:63]
	v_mfma_f32_16x16x32_bf16 v[56:59], v[132:135], v[28:31], v[56:59]
	v_mfma_f32_16x16x32_bf16 v[60:63], v[174:177], v[28:31], v[60:63]
	s_barrier
; __device__ __forceinline__ f32x4 mfma16(bf16x8 a, bf16x8 b, f32x4 c) { return __builtin_amdgcn_mfma_f32_16x16x32_bf16(a, b, c, 0, 0, 0); }
; __device__ __forceinline__ void mem_task(bf16_t* zb, const bf16_t* kvm_b, const bf16_t* vmt_b, int hm, int t0, int lane, bool do_store) {
;     ...
;     for (int kt = 0; kt < 16; ++kt) {
;         if (kt + 2 < 16) { const bf16_t* kp = kbase + (size_t)(((kt + 2) >> 1) * 32 + 4 * ((kt + 2) & 1)) * 2048;
; #pragma unroll
;             for (int kk = 0; kk < 8; ++kk) kfr[(kt + 2) % 3][kk] = *(const bf16x8*)(kp + kk * 32); }
;         f32x4 acc = zero4;
;         __builtin_amdgcn_s_setprio(1);
; #pragma unroll
;         for (int kk = 0; kk < 8; ++kk) acc = mfma16(kfr[kt % 3][kk], qf[kk], acc);
;         __builtin_amdgcn_s_setprio(0);
;         s[kt] = acc; }
	s_add_i32 m0, s7, 32768
	s_nop 0
	global_load_lds_dwordx4 v[182:183], off
	v_lshl_add_u64 v[182:183], v[182:183], 0, s[98:99]
	s_add_i32 m0, s7, 40960
	s_nop 0
	global_load_lds_dwordx4 v[182:183], off
	v_lshl_add_u64 v[182:183], v[182:183], 0, s[98:99]
	ds_read_b128 v[104:107], v179 offset:0
	ds_read_b128 v[146:149], v179 offset:8192
	ds_read_b128 v[108:111], v179 offset:1024
	ds_read_b128 v[150:153], v179 offset:9216
	ds_read_b128 v[112:115], v179 offset:2048
	ds_read_b128 v[154:157], v179 offset:10240
	ds_read_b128 v[116:119], v179 offset:3072
	ds_read_b128 v[158:161], v179 offset:11264
	ds_read_b128 v[120:123], v179 offset:4096
	ds_read_b128 v[162:165], v179 offset:12288
	ds_read_b128 v[124:127], v179 offset:5120
	ds_read_b128 v[166:169], v179 offset:13312
	ds_read_b128 v[128:131], v179 offset:6144
	ds_read_b128 v[170:173], v179 offset:14336
	ds_read_b128 v[132:135], v179 offset:7168
	ds_read_b128 v[174:177], v179 offset:15360
	s_waitcnt lgkmcnt(0)
	s_waitcnt vmcnt(10)
	s_barrier
	v_mfma_f32_16x16x32_bf16 v[72:75], v[104:107], v[0:3], 0
	v_mfma_f32_16x16x32_bf16 v[76:79], v[146:149], v[0:3], 0
	v_mfma_f32_16x16x32_bf16 v[72:75], v[108:111], v[4:7], v[72:75]
	v_mfma_f32_16x16x32_bf16 v[76:79], v[150:153], v[4:7], v[76:79]
	v_mfma_f32_16x16x32_bf16 v[72:75], v[112:115], v[8:11], v[72:75]
	v_mfma_f32_16x16x32_bf16 v[76:79], v[154:157], v[8:11], v[76:79]
	v_mfma_f32_16x16x32_bf16 v[72:75], v[116:119], v[12:15], v[72:75]
	v_mfma_f32_16x16x32_bf16 v[76:79], v[158:161], v[12:15], v[76:79]
	v_mfma_f32_16x16x32_bf16 v[72:75], v[120:123], v[16:19], v[72:75]
	v_mfma_f32_16x16x32_bf16 v[76:79], v[162:165], v[16:19], v[76:79]
	v_mfma_f32_16x16x32_bf16 v[72:75], v[124:127], v[20:23], v[72:75]
	v_mfma_f32_16x16x32_bf16 v[76:79], v[166:169], v[20:23], v[76:79]
	v_mfma_f32_16x16x32_bf16 v[72:75], v[128:131], v[24:27], v[72:75]
	v_mfma_f32_16x16x32_bf16 v[76:79], v[170:173], v[24:27], v[76:79]
	v_mfma_f32_16x16x32_bf16 v[72:75], v[132:135], v[28:31], v[72:75]
	v_mfma_f32_16x16x32_bf16 v[76:79], v[174:177], v[28:31], v[76:79]
	s_barrier
	s_add_i32 m0, s7, 49152
	s_nop 0
	global_load_lds_dwordx4 v[182:183], off
	v_lshl_add_u64 v[182:183], v[182:183], 0, s[98:99]
	s_add_i32 m0, s7, 57344
	s_nop 0
	global_load_lds_dwordx4 v[182:183], off
	v_lshl_add_u64 v[182:183], v[182:183], 0, s[98:99]
	ds_read_b128 v[104:107], v179 offset:16384
	ds_read_b128 v[146:149], v179 offset:24576
	ds_read_b128 v[108:111], v179 offset:17408
	ds_read_b128 v[150:153], v179 offset:25600
	ds_read_b128 v[112:115], v179 offset:18432
	ds_read_b128 v[154:157], v179 offset:26624
	ds_read_b128 v[116:119], v179 offset:19456
	ds_read_b128 v[158:161], v179 offset:27648
	ds_read_b128 v[120:123], v179 offset:20480
	ds_read_b128 v[162:165], v179 offset:28672
	ds_read_b128 v[124:127], v179 offset:21504
	ds_read_b128 v[166:169], v179 offset:29696
	ds_read_b128 v[128:131], v179 offset:22528
	ds_read_b128 v[170:173], v179 offset:30720
	ds_read_b128 v[132:135], v179 offset:23552
	ds_read_b128 v[174:177], v179 offset:31744
	s_waitcnt lgkmcnt(0)
	s_waitcnt vmcnt(10)
	s_barrier
	v_mfma_f32_16x16x32_bf16 v[80:83], v[104:107], v[0:3], 0
	v_mfma_f32_16x16x32_bf16 v[84:87], v[146:149], v[0:3], 0
	v_mfma_f32_16x16x32_bf16 v[80:83], v[108:111], v[4:7], v[80:83]
	v_mfma_f32_16x16x32_bf16 v[84:87], v[150:153], v[4:7], v[84:87]
	v_mfma_f32_16x16x32_bf16 v[80:83], v[112:115], v[8:11], v[80:83]
	v_mfma_f32_16x16x32_bf16 v[84:87], v[154:157], v[8:11], v[84:87]
	v_mfma_f32_16x16x32_bf16 v[80:83], v[116:119], v[12:15], v[80:83]
	v_mfma_f32_16x16x32_bf16 v[84:87], v[158:161], v[12:15], v[84:87]
	v_mfma_f32_16x16x32_bf16 v[80:83], v[120:123], v[16:19], v[80:83]
	v_mfma_f32_16x16x32_bf16 v[84:87], v[162:165], v[16:19], v[84:87]
	v_mfma_f32_16x16x32_bf16 v[80:83], v[124:127], v[20:23], v[80:83]
	v_mfma_f32_16x16x32_bf16 v[84:87], v[166:169], v[20:23], v[84:87]
	v_mfma_f32_16x16x32_bf16 v[80:83], v[128:131], v[24:27], v[80:83]
	v_mfma_f32_16x16x32_bf16 v[84:87], v[170:173], v[24:27], v[84:87]
	v_mfma_f32_16x16x32_bf16 v[80:83], v[132:135], v[28:31], v[80:83]
	v_mfma_f32_16x16x32_bf16 v[84:87], v[174:177], v[28:31], v[84:87]
	s_barrier
	s_add_i32 m0, s7, 65536
	s_nop 0
	global_load_lds_dwordx4 v[182:183], off
	v_lshl_add_u64 v[182:183], v[182:183], 0, s[98:99]
	s_add_i32 m0, s7, 73728
	s_nop 0
	global_load_lds_dwordx4 v[182:183], off
	v_lshl_add_u64 v[182:183], v[182:183], 0, s[98:99]
	ds_read_b128 v[104:107], v179 offset:32768
	ds_read_b128 v[146:149], v179 offset:40960
	ds_read_b128 v[108:111], v179 offset:33792
	ds_read_b128 v[150:153], v179 offset:41984
	ds_read_b128 v[112:115], v179 offset:34816
	ds_read_b128 v[154:157], v179 offset:43008
	ds_read_b128 v[116:119], v179 offset:35840
	ds_read_b128 v[158:161], v179 offset:44032
	ds_read_b128 v[120:123], v179 offset:36864
	ds_read_b128 v[162:165], v179 offset:45056
	ds_read_b128 v[124:127], v179 offset:37888
	ds_read_b128 v[166:169], v179 offset:46080
	ds_read_b128 v[128:131], v179 offset:38912
	ds_read_b128 v[170:173], v179 offset:47104
	ds_read_b128 v[132:135], v179 offset:39936
	ds_read_b128 v[174:177], v179 offset:48128
	s_waitcnt lgkmcnt(0)
	s_waitcnt vmcnt(10)
	s_barrier
; __device__ __forceinline__ f32x4 mfma16(bf16x8 a, bf16x8 b, f32x4 c) { return __builtin_amdgcn_mfma_f32_16x16x32_bf16(a, b, c, 0, 0, 0); }
; __device__ __forceinline__ void mem_task(bf16_t* zb, const bf16_t* kvm_b, const bf16_t* vmt_b, int hm, int t0, int lane, bool do_store) {
;     ...
;     for (int kt = 0; kt < 16; ++kt) {
;         if (kt + 2 < 16) { const bf16_t* kp = kbase + (size_t)(((kt + 2) >> 1) * 32 + 4 * ((kt + 2) & 1)) * 2048;
; #pragma unroll
;             for (int kk = 0; kk < 8; ++kk) kfr[(kt + 2) % 3][kk] = *(const bf16x8*)(kp + kk * 32); }
;         f32x4 acc = zero4;
;         __builtin_amdgcn_s_setprio(1);
; #pragma unroll
;         for (int kk = 0; kk < 8; ++kk) acc = mfma16(kfr[kt % 3][kk], qf[kk], acc);
;         __builtin_amdgcn_s_setprio(0);
;         s[kt] = acc; }
;     float l = 0.f;
; #pragma unroll
;     for (int kt = 0; kt < 16; ++kt)
; #pragma unroll
;         for (int j = 0; j < 4; ++j) { s[kt][j] = __builtin_amdgcn_exp2f(s[kt][j]); l += s[kt][j]; }
	v_mfma_f32_16x16x32_bf16 v[88:91], v[104:107], v[0:3], 0
	v_mfma_f32_16x16x32_bf16 v[92:95], v[146:149], v[0:3], 0
	v_mfma_f32_16x16x32_bf16 v[88:91], v[108:111], v[4:7], v[88:91]
	v_mfma_f32_16x16x32_bf16 v[92:95], v[150:153], v[4:7], v[92:95]
	v_mfma_f32_16x16x32_bf16 v[88:91], v[112:115], v[8:11], v[88:91]
	v_mfma_f32_16x16x32_bf16 v[92:95], v[154:157], v[8:11], v[92:95]
	v_mfma_f32_16x16x32_bf16 v[88:91], v[116:119], v[12:15], v[88:91]
	v_mfma_f32_16x16x32_bf16 v[92:95], v[158:161], v[12:15], v[92:95]
	v_mfma_f32_16x16x32_bf16 v[88:91], v[120:123], v[16:19], v[88:91]
	v_mfma_f32_16x16x32_bf16 v[92:95], v[162:165], v[16:19], v[92:95]
	v_mfma_f32_16x16x32_bf16 v[88:91], v[124:127], v[20:23], v[88:91]
	v_mfma_f32_16x16x32_bf16 v[92:95], v[166:169], v[20:23], v[92:95]
	v_mfma_f32_16x16x32_bf16 v[88:91], v[128:131], v[24:27], v[88:91]
	v_mfma_f32_16x16x32_bf16 v[92:95], v[170:173], v[24:27], v[92:95]
	v_mfma_f32_16x16x32_bf16 v[88:91], v[132:135], v[28:31], v[88:91]
	v_mfma_f32_16x16x32_bf16 v[92:95], v[174:177], v[28:31], v[92:95]
	s_barrier
	s_add_i32 m0, s7, 81920
	s_nop 0
	global_load_lds_dwordx4 v[182:183], off
	v_lshl_add_u64 v[182:183], v[182:183], 0, s[98:99]
	s_add_i32 m0, s7, 90112
	s_nop 0
	global_load_lds_dwordx4 v[182:183], off
	v_lshl_add_u64 v[182:183], v[182:183], 0, s[98:99]
	ds_read_b128 v[104:107], v179 offset:49152
	ds_read_b128 v[146:149], v179 offset:57344
	ds_read_b128 v[108:111], v179 offset:50176
	ds_read_b128 v[150:153], v179 offset:58368
	ds_read_b128 v[112:115], v179 offset:51200
	ds_read_b128 v[154:157], v179 offset:59392
	ds_read_b128 v[116:119], v179 offset:52224
	ds_read_b128 v[158:161], v179 offset:60416
	ds_read_b128 v[120:123], v179 offset:53248
	ds_read_b128 v[162:165], v179 offset:61440
	ds_read_b128 v[124:127], v179 offset:54272
	ds_read_b128 v[166:169], v179 offset:62464
	ds_read_b128 v[128:131], v179 offset:55296
	ds_read_b128 v[170:173], v179 offset:63488
	ds_read_b128 v[132:135], v179 offset:56320
	ds_read_b128 v[174:177], v179 offset:64512
	s_waitcnt lgkmcnt(0)
	s_waitcnt vmcnt(10)
	s_barrier
	v_mfma_f32_16x16x32_bf16 v[96:99], v[104:107], v[0:3], 0
	v_mfma_f32_16x16x32_bf16 v[100:103], v[146:149], v[0:3], 0
	v_mfma_f32_16x16x32_bf16 v[96:99], v[108:111], v[4:7], v[96:99]
	v_mfma_f32_16x16x32_bf16 v[100:103], v[150:153], v[4:7], v[100:103]
	v_mfma_f32_16x16x32_bf16 v[96:99], v[112:115], v[8:11], v[96:99]
	v_mfma_f32_16x16x32_bf16 v[100:103], v[154:157], v[8:11], v[100:103]
	v_mfma_f32_16x16x32_bf16 v[96:99], v[116:119], v[12:15], v[96:99]
	v_mfma_f32_16x16x32_bf16 v[100:103], v[158:161], v[12:15], v[100:103]
	v_mfma_f32_16x16x32_bf16 v[96:99], v[120:123], v[16:19], v[96:99]
	v_mfma_f32_16x16x32_bf16 v[100:103], v[162:165], v[16:19], v[100:103]
	v_mfma_f32_16x16x32_bf16 v[96:99], v[124:127], v[20:23], v[96:99]
	v_mfma_f32_16x16x32_bf16 v[100:103], v[166:169], v[20:23], v[100:103]
	v_mfma_f32_16x16x32_bf16 v[96:99], v[128:131], v[24:27], v[96:99]
	v_mfma_f32_16x16x32_bf16 v[100:103], v[170:173], v[24:27], v[100:103]
	v_mfma_f32_16x16x32_bf16 v[96:99], v[132:135], v[28:31], v[96:99]
	v_mfma_f32_16x16x32_bf16 v[100:103], v[174:177], v[28:31], v[100:103]
	s_nop 7
	s_nop 7
	v_exp_f32_e32 v32, v32
	v_exp_f32_e32 v33, v33
	v_add_f32_e32 v190, 0, v32
	v_exp_f32_e32 v34, v34
	v_add_f32_e32 v190, v190, v33
	v_exp_f32_e32 v35, v35
	v_add_f32_e32 v190, v190, v34
	v_exp_f32_e32 v36, v36
	v_add_f32_e32 v190, v190, v35
	v_exp_f32_e32 v37, v37
	v_add_f32_e32 v190, v190, v36
	v_exp_f32_e32 v38, v38
	v_add_f32_e32 v190, v190, v37
	v_exp_f32_e32 v39, v39
	v_add_f32_e32 v190, v190, v38
	v_exp_f32_e32 v40, v40
	v_add_f32_e32 v190, v190, v39
	v_exp_f32_e32 v41, v41
	v_add_f32_e32 v190, v190, v40
	v_exp_f32_e32 v42, v42
	v_add_f32_e32 v190, v190, v41
	v_exp_f32_e32 v43, v43
	v_add_f32_e32 v190, v190, v42
	v_exp_f32_e32 v44, v44
	v_add_f32_e32 v190, v190, v43
	v_exp_f32_e32 v45, v45
	v_add_f32_e32 v190, v190, v44
	v_exp_f32_e32 v46, v46
	v_add_f32_e32 v190, v190, v45
	v_exp_f32_e32 v47, v47
	v_add_f32_e32 v190, v190, v46
	v_exp_f32_e32 v48, v48
	v_add_f32_e32 v190, v190, v47
	v_exp_f32_e32 v49, v49
	v_add_f32_e32 v190, v190, v48
	v_exp_f32_e32 v50, v50
	v_add_f32_e32 v190, v190, v49
	v_exp_f32_e32 v51, v51
	v_add_f32_e32 v190, v190, v50
	v_exp_f32_e32 v52, v52
	v_add_f32_e32 v190, v190, v51
	v_exp_f32_e32 v53, v53
	v_add_f32_e32 v190, v190, v52
	v_exp_f32_e32 v54, v54
	v_add_f32_e32 v190, v190, v53
	v_exp_f32_e32 v55, v55
	v_add_f32_e32 v190, v190, v54
	v_exp_f32_e32 v56, v56
	v_add_f32_e32 v190, v190, v55
	v_exp_f32_e32 v57, v57
	v_add_f32_e32 v190, v190, v56
	v_exp_f32_e32 v58, v58
	v_add_f32_e32 v190, v190, v57
	v_exp_f32_e32 v59, v59
	v_add_f32_e32 v190, v190, v58
	v_exp_f32_e32 v60, v60
	v_add_f32_e32 v190, v190, v59
	v_exp_f32_e32 v61, v61
	v_add_f32_e32 v190, v190, v60
	v_exp_f32_e32 v62, v62
	v_add_f32_e32 v190, v190, v61
	v_exp_f32_e32 v63, v63
	v_add_f32_e32 v190, v190, v62
	v_exp_f32_e32 v72, v72
	v_add_f32_e32 v190, v190, v63
	v_exp_f32_e32 v73, v73
	v_add_f32_e32 v190, v190, v72
	v_exp_f32_e32 v74, v74
	v_add_f32_e32 v190, v190, v73
	v_exp_f32_e32 v75, v75
	v_add_f32_e32 v190, v190, v74
	v_exp_f32_e32 v76, v76
	v_add_f32_e32 v190, v190, v75
	v_exp_f32_e32 v77, v77
	v_add_f32_e32 v190, v190, v76
	v_exp_f32_e32 v78, v78
	v_add_f32_e32 v190, v190, v77
	v_exp_f32_e32 v79, v79
	v_add_f32_e32 v190, v190, v78
	v_exp_f32_e32 v80, v80
	v_add_f32_e32 v190, v190, v79
	v_exp_f32_e32 v81, v81
	v_add_f32_e32 v190, v190, v80
	v_exp_f32_e32 v82, v82
	v_add_f32_e32 v190, v190, v81
	v_exp_f32_e32 v83, v83
	v_add_f32_e32 v190, v190, v82
	v_exp_f32_e32 v84, v84
	v_add_f32_e32 v190, v190, v83
	v_exp_f32_e32 v85, v85
; __device__ __forceinline__ unsigned cvt_pk_bf16(float lo, float hi) { unsigned r; asm volatile("v_cvt_pk_bf16_f32 %0, %1, %2" : "=v"(r) : "v"(lo), "v"(hi)); return r; }
; __device__ __forceinline__ f32x4 mfma16(bf16x8 a, bf16x8 b, f32x4 c) { return __builtin_amdgcn_mfma_f32_16x16x32_bf16(a, b, c, 0, 0, 0); }
; __device__ __forceinline__ float x16sum(float x) { auto r = __builtin_amdgcn_permlane16_swap(__float_as_uint(x), __float_as_uint(x), false, false); return __uint_as_float(r[0]) + __uint_as_float(r[1]); }
; __device__ __forceinline__ float x32sum(float x) { auto r = __builtin_amdgcn_permlane32_swap(__float_as_uint(x), __float_as_uint(x), false, false); return __uint_as_float(r[0]) + __uint_as_float(r[1]); }
; __device__ __forceinline__ void mem_task(bf16_t* zb, const bf16_t* kvm_b, const bf16_t* vmt_b, int hm, int t0, int lane, bool do_store) {
;     ...
;         for (int j = 0; j < 4; ++j) { s[kt][j] = __builtin_amdgcn_exp2f(s[kt][j]); l += s[kt][j]; }
;     l = x16sum(l); l = x32sum(l);
;     const float il = 1.0f / l;
;     bf16x8 pf[8];
; #pragma unroll
;     for (int kp = 0; kp < 8; ++kp) { u32x4 w; w.x = cvt_pk_bf16(s[2 * kp][0], s[2 * kp][1]); w.y = cvt_pk_bf16(s[2 * kp][2], s[2 * kp][3]); w.z = cvt_pk_bf16(s[2 * kp + 1][0], s[2 * kp + 1][1]); w.w = cvt_pk_bf16(s[2 * kp + 1][2], s[2 * kp + 1][3]); pf[kp] = __builtin_bit_cast(bf16x8, w); }
;     const bf16_t* vbase = vmt_b + (size_t)(hm * 256 + n) * 256 + 8 * fq;
;     bf16x8 vfr[3][8];
; #pragma unroll
;     for (int kp = 0; kp < 8; ++kp) vfr[0][kp] = *(const bf16x8*)(vbase + kp * 32);
;     { const bf16_t* vp = vbase + (size_t)16 * 256;
; #pragma unroll
;       for (int kp = 0; kp < 8; ++kp) vfr[1][kp] = *(const bf16x8*)(vp + kp * 32); }
; #pragma unroll
;     for (int dt = 0; dt < 16; ++dt) {
;         if (dt + 2 < 16) { const bf16_t* vp = vbase + (size_t)((dt + 2) * 16) * 256;
; #pragma unroll
;             for (int kp = 0; kp < 8; ++kp) vfr[(dt + 2) % 3][kp] = *(const bf16x8*)(vp + kp * 32); }
;         f32x4 acc = zero4;
;         __builtin_amdgcn_s_setprio(1);
; #pragma unroll
;         for (int kp = 0; kp < 8; ++kp) acc = mfma16(vfr[dt % 3][kp], pf[kp], acc);
;         __builtin_amdgcn_s_setprio(0);
;         u32x2 w; w.x = cvt_pk_bf16(acc[0] * il, acc[1] * il); w.y = cvt_pk_bf16(acc[2] * il, acc[3] * il); if (do_store || acc[0] == 12345.678f) *(u32x2*)(qp + dt * 16 + 4 * fq) = w; }
	v_add_f32_e32 v190, v190, v84
	v_exp_f32_e32 v86, v86
	v_add_f32_e32 v190, v190, v85
	v_exp_f32_e32 v87, v87
	v_add_f32_e32 v190, v190, v86
	v_exp_f32_e32 v88, v88
	v_add_f32_e32 v190, v190, v87
	v_exp_f32_e32 v89, v89
	v_add_f32_e32 v190, v190, v88
	v_exp_f32_e32 v90, v90
	v_add_f32_e32 v190, v190, v89
	v_exp_f32_e32 v91, v91
	v_add_f32_e32 v190, v190, v90
	v_exp_f32_e32 v92, v92
	v_add_f32_e32 v190, v190, v91
	v_exp_f32_e32 v93, v93
	v_add_f32_e32 v190, v190, v92
	v_exp_f32_e32 v94, v94
	v_add_f32_e32 v190, v190, v93
	v_exp_f32_e32 v95, v95
	v_add_f32_e32 v190, v190, v94
	v_exp_f32_e32 v96, v96
	v_add_f32_e32 v190, v190, v95
	v_exp_f32_e32 v97, v97
	v_add_f32_e32 v190, v190, v96
	v_exp_f32_e32 v98, v98
	v_add_f32_e32 v190, v190, v97
	v_exp_f32_e32 v99, v99
	v_add_f32_e32 v190, v190, v98
	v_exp_f32_e32 v100, v100
	v_add_f32_e32 v190, v190, v99
	v_exp_f32_e32 v101, v101
	v_add_f32_e32 v190, v190, v100
	v_exp_f32_e32 v102, v102
	v_add_f32_e32 v190, v190, v101
	v_exp_f32_e32 v103, v103
	v_add_f32_e32 v190, v190, v102
	s_nop 0
	v_add_f32_e32 v190, v190, v103
	v_mov_b32_e32 v186, v190
	s_nop 1
	v_permlane16_swap_b32_e32 v190, v186
	v_add_f32_e32 v190, v190, v186
	v_mov_b32_e32 v186, v190
	s_nop 1
	v_permlane32_swap_b32_e32 v190, v186
	v_add_f32_e32 v190, v190, v186
	v_div_scale_f32 v186, s[12:13], v190, v190, 1.0
	v_rcp_f32_e32 v187, v186
	s_nop 0
	v_fma_f32 v188, -v186, v187, 1.0
	v_fmac_f32_e32 v187, v188, v187
	v_div_scale_f32 v188, vcc, 1.0, v190, 1.0
	v_mul_f32_e32 v189, v188, v187
	v_fma_f32 v136, -v186, v189, v188
	v_fmac_f32_e32 v189, v136, v187
	v_fma_f32 v186, -v186, v189, v188
	s_nop 0
	v_div_fmas_f32 v186, v186, v187, v189
	v_div_fixup_f32 v191, v186, v190, 1.0
	v_cvt_pk_bf16_f32 v32, v32, v33
	v_cvt_pk_bf16_f32 v33, v34, v35
	v_cvt_pk_bf16_f32 v34, v36, v37
	v_cvt_pk_bf16_f32 v35, v38, v39
	v_cvt_pk_bf16_f32 v40, v40, v41
	v_cvt_pk_bf16_f32 v41, v42, v43
	v_cvt_pk_bf16_f32 v42, v44, v45
	v_cvt_pk_bf16_f32 v43, v46, v47
	v_cvt_pk_bf16_f32 v48, v48, v49
	v_cvt_pk_bf16_f32 v49, v50, v51
	v_cvt_pk_bf16_f32 v50, v52, v53
	v_cvt_pk_bf16_f32 v51, v54, v55
	v_cvt_pk_bf16_f32 v56, v56, v57
	v_cvt_pk_bf16_f32 v57, v58, v59
	v_cvt_pk_bf16_f32 v58, v60, v61
	v_cvt_pk_bf16_f32 v59, v62, v63
	v_cvt_pk_bf16_f32 v72, v72, v73
	v_cvt_pk_bf16_f32 v73, v74, v75
	v_cvt_pk_bf16_f32 v74, v76, v77
	v_cvt_pk_bf16_f32 v75, v78, v79
	v_cvt_pk_bf16_f32 v80, v80, v81
	v_cvt_pk_bf16_f32 v81, v82, v83
	v_cvt_pk_bf16_f32 v82, v84, v85
	v_cvt_pk_bf16_f32 v83, v86, v87
	v_cvt_pk_bf16_f32 v88, v88, v89
	v_cvt_pk_bf16_f32 v89, v90, v91
	v_cvt_pk_bf16_f32 v90, v92, v93
	v_cvt_pk_bf16_f32 v91, v94, v95
	v_cvt_pk_bf16_f32 v96, v96, v97
	v_cvt_pk_bf16_f32 v97, v98, v99
	v_cvt_pk_bf16_f32 v98, v100, v101
	v_cvt_pk_bf16_f32 v99, v102, v103
	s_barrier
	s_add_i32 m0, s7, 98304
	s_nop 0
	global_load_lds_dwordx4 v[182:183], off
	v_lshl_add_u64 v[182:183], v[182:183], 0, s[98:99]
	s_add_i32 m0, s7, 106496
	s_nop 0
	global_load_lds_dwordx4 v[182:183], off
	v_lshl_add_u64 v[182:183], v[182:183], 0, s[98:99]
	ds_read_b128 v[104:107], v178 offset:0
	ds_read_b128 v[146:149], v178 offset:8192
	ds_read_b128 v[108:111], v178 offset:1024
	ds_read_b128 v[150:153], v178 offset:9216
	ds_read_b128 v[112:115], v178 offset:2048
	ds_read_b128 v[154:157], v178 offset:10240
	ds_read_b128 v[116:119], v178 offset:3072
	ds_read_b128 v[158:161], v178 offset:11264
	ds_read_b128 v[120:123], v178 offset:4096
	ds_read_b128 v[162:165], v178 offset:12288
	ds_read_b128 v[124:127], v178 offset:5120
	ds_read_b128 v[166:169], v178 offset:13312
	ds_read_b128 v[128:131], v178 offset:6144
	ds_read_b128 v[170:173], v178 offset:14336
	ds_read_b128 v[132:135], v178 offset:7168
	ds_read_b128 v[174:177], v178 offset:15360
	s_waitcnt lgkmcnt(0)
	s_waitcnt vmcnt(10)
	s_barrier
	v_mfma_f32_16x16x32_bf16 v[192:195], v[104:107], v[32:35], 0
	v_mfma_f32_16x16x32_bf16 v[196:199], v[146:149], v[32:35], 0
	v_mfma_f32_16x16x32_bf16 v[192:195], v[108:111], v[40:43], v[192:195]
	v_mfma_f32_16x16x32_bf16 v[196:199], v[150:153], v[40:43], v[196:199]
	v_mfma_f32_16x16x32_bf16 v[192:195], v[112:115], v[48:51], v[192:195]
	v_mfma_f32_16x16x32_bf16 v[196:199], v[154:157], v[48:51], v[196:199]
	v_mfma_f32_16x16x32_bf16 v[192:195], v[116:119], v[56:59], v[192:195]
	v_mfma_f32_16x16x32_bf16 v[196:199], v[158:161], v[56:59], v[196:199]
	v_mfma_f32_16x16x32_bf16 v[192:195], v[120:123], v[72:75], v[192:195]
	v_mfma_f32_16x16x32_bf16 v[196:199], v[162:165], v[72:75], v[196:199]
	v_mfma_f32_16x16x32_bf16 v[192:195], v[124:127], v[80:83], v[192:195]
	v_mfma_f32_16x16x32_bf16 v[196:199], v[166:169], v[80:83], v[196:199]
	v_mfma_f32_16x16x32_bf16 v[192:195], v[128:131], v[88:91], v[192:195]
	v_mfma_f32_16x16x32_bf16 v[196:199], v[170:173], v[88:91], v[196:199]
	v_mfma_f32_16x16x32_bf16 v[192:195], v[132:135], v[96:99], v[192:195]
	v_mfma_f32_16x16x32_bf16 v[196:199], v[174:177], v[96:99], v[196:199]
	s_barrier
	s_add_i32 m0, s7, 114688
	s_nop 0
	global_load_lds_dwordx4 v[182:183], off
	v_lshl_add_u64 v[182:183], v[182:183], 0, s[98:99]
	s_add_i32 m0, s7, 122880
	s_nop 0
	global_load_lds_dwordx4 v[182:183], off
	v_lshl_add_u64 v[182:183], v[182:183], 0, s[98:99]
	ds_read_b128 v[104:107], v178 offset:16384
	ds_read_b128 v[146:149], v178 offset:24576
	ds_read_b128 v[108:111], v178 offset:17408
	ds_read_b128 v[150:153], v178 offset:25600
	ds_read_b128 v[112:115], v178 offset:18432
	ds_read_b128 v[154:157], v178 offset:26624
	ds_read_b128 v[116:119], v178 offset:19456
	ds_read_b128 v[158:161], v178 offset:27648
	ds_read_b128 v[120:123], v178 offset:20480
	ds_read_b128 v[162:165], v178 offset:28672
	ds_read_b128 v[124:127], v178 offset:21504
	ds_read_b128 v[166:169], v178 offset:29696
	ds_read_b128 v[128:131], v178 offset:22528
	ds_read_b128 v[170:173], v178 offset:30720
	ds_read_b128 v[132:135], v178 offset:23552
	ds_read_b128 v[174:177], v178 offset:31744
	s_waitcnt lgkmcnt(0)
	s_waitcnt vmcnt(10)
	s_barrier
; __device__ __forceinline__ unsigned cvt_pk_bf16(float lo, float hi) { unsigned r; asm volatile("v_cvt_pk_bf16_f32 %0, %1, %2" : "=v"(r) : "v"(lo), "v"(hi)); return r; }
; __device__ __forceinline__ f32x4 mfma16(bf16x8 a, bf16x8 b, f32x4 c) { return __builtin_amdgcn_mfma_f32_16x16x32_bf16(a, b, c, 0, 0, 0); }
; __device__ __forceinline__ void mem_task(bf16_t* zb, const bf16_t* kvm_b, const bf16_t* vmt_b, int hm, int t0, int lane, bool do_store) {
;     ...
; #pragma unroll
;     for (int dt = 0; dt < 16; ++dt) {
;         if (dt + 2 < 16) { const bf16_t* vp = vbase + (size_t)((dt + 2) * 16) * 256;
; #pragma unroll
;             for (int kp = 0; kp < 8; ++kp) vfr[(dt + 2) % 3][kp] = *(const bf16x8*)(vp + kp * 32); }
;         f32x4 acc = zero4;
;         __builtin_amdgcn_s_setprio(1);
; #pragma unroll
;         for (int kp = 0; kp < 8; ++kp) acc = mfma16(vfr[dt % 3][kp], pf[kp], acc);
;         __builtin_amdgcn_s_setprio(0);
;         u32x2 w; w.x = cvt_pk_bf16(acc[0] * il, acc[1] * il); w.y = cvt_pk_bf16(acc[2] * il, acc[3] * il); if (do_store || acc[0] == 12345.678f) *(u32x2*)(qp + dt * 16 + 4 * fq) = w; }
	v_mfma_f32_16x16x32_bf16 v[206:209], v[104:107], v[32:35], 0
	v_mfma_f32_16x16x32_bf16 v[210:213], v[146:149], v[32:35], 0
	v_mfma_f32_16x16x32_bf16 v[206:209], v[108:111], v[40:43], v[206:209]
	v_mfma_f32_16x16x32_bf16 v[210:213], v[150:153], v[40:43], v[210:213]
	v_mfma_f32_16x16x32_bf16 v[206:209], v[112:115], v[48:51], v[206:209]
	v_mfma_f32_16x16x32_bf16 v[210:213], v[154:157], v[48:51], v[210:213]
	v_mfma_f32_16x16x32_bf16 v[206:209], v[116:119], v[56:59], v[206:209]
	v_mfma_f32_16x16x32_bf16 v[210:213], v[158:161], v[56:59], v[210:213]
	v_mfma_f32_16x16x32_bf16 v[206:209], v[120:123], v[72:75], v[206:209]
	v_mfma_f32_16x16x32_bf16 v[210:213], v[162:165], v[72:75], v[210:213]
	v_mfma_f32_16x16x32_bf16 v[206:209], v[124:127], v[80:83], v[206:209]
	v_mfma_f32_16x16x32_bf16 v[210:213], v[166:169], v[80:83], v[210:213]
	v_mfma_f32_16x16x32_bf16 v[206:209], v[128:131], v[88:91], v[206:209]
	v_mfma_f32_16x16x32_bf16 v[210:213], v[170:173], v[88:91], v[210:213]
	v_mfma_f32_16x16x32_bf16 v[206:209], v[132:135], v[96:99], v[206:209]
	v_mfma_f32_16x16x32_bf16 v[210:213], v[174:177], v[96:99], v[210:213]
	v_mul_f32_e32 v192, v191, v192
	v_mul_f32_e32 v193, v191, v193
	v_mul_f32_e32 v194, v191, v194
	v_mul_f32_e32 v195, v191, v195
	v_cvt_pk_bf16_f32 v192, v192, v193
	v_cvt_pk_bf16_f32 v193, v194, v195
	global_store_dwordx2 v[184:185], v[192:193], off
	v_mul_f32_e32 v196, v191, v196
	v_mul_f32_e32 v197, v191, v197
	v_mul_f32_e32 v198, v191, v198
	v_mul_f32_e32 v199, v191, v199
	v_cvt_pk_bf16_f32 v196, v196, v197
	v_cvt_pk_bf16_f32 v197, v198, v199
	global_store_dwordx2 v[184:185], v[196:197], off offset:32
	s_barrier
	ds_read_b128 v[104:107], v178 offset:32768
	ds_read_b128 v[146:149], v178 offset:40960
	ds_read_b128 v[108:111], v178 offset:33792
	ds_read_b128 v[150:153], v178 offset:41984
	ds_read_b128 v[112:115], v178 offset:34816
	ds_read_b128 v[154:157], v178 offset:43008
	ds_read_b128 v[116:119], v178 offset:35840
	ds_read_b128 v[158:161], v178 offset:44032
	ds_read_b128 v[120:123], v178 offset:36864
	ds_read_b128 v[162:165], v178 offset:45056
	ds_read_b128 v[124:127], v178 offset:37888
	ds_read_b128 v[166:169], v178 offset:46080
	ds_read_b128 v[128:131], v178 offset:38912
	ds_read_b128 v[170:173], v178 offset:47104
	ds_read_b128 v[132:135], v178 offset:39936
	ds_read_b128 v[174:177], v178 offset:48128
	s_waitcnt lgkmcnt(0)
	s_waitcnt vmcnt(10)
	s_barrier
	v_mfma_f32_16x16x32_bf16 v[192:195], v[104:107], v[32:35], 0
	v_mfma_f32_16x16x32_bf16 v[196:199], v[146:149], v[32:35], 0
	v_mfma_f32_16x16x32_bf16 v[192:195], v[108:111], v[40:43], v[192:195]
	v_mfma_f32_16x16x32_bf16 v[196:199], v[150:153], v[40:43], v[196:199]
	v_mfma_f32_16x16x32_bf16 v[192:195], v[112:115], v[48:51], v[192:195]
	v_mfma_f32_16x16x32_bf16 v[196:199], v[154:157], v[48:51], v[196:199]
	v_mfma_f32_16x16x32_bf16 v[192:195], v[116:119], v[56:59], v[192:195]
	v_mfma_f32_16x16x32_bf16 v[196:199], v[158:161], v[56:59], v[196:199]
	v_mfma_f32_16x16x32_bf16 v[192:195], v[120:123], v[72:75], v[192:195]
	v_mfma_f32_16x16x32_bf16 v[196:199], v[162:165], v[72:75], v[196:199]
	v_mfma_f32_16x16x32_bf16 v[192:195], v[124:127], v[80:83], v[192:195]
	v_mfma_f32_16x16x32_bf16 v[196:199], v[166:169], v[80:83], v[196:199]
	v_mfma_f32_16x16x32_bf16 v[192:195], v[128:131], v[88:91], v[192:195]
	v_mfma_f32_16x16x32_bf16 v[196:199], v[170:173], v[88:91], v[196:199]
	v_mfma_f32_16x16x32_bf16 v[192:195], v[132:135], v[96:99], v[192:195]
	v_mfma_f32_16x16x32_bf16 v[196:199], v[174:177], v[96:99], v[196:199]
	v_mul_f32_e32 v206, v191, v206
	v_mul_f32_e32 v207, v191, v207
	v_mul_f32_e32 v208, v191, v208
	v_mul_f32_e32 v209, v191, v209
	v_cvt_pk_bf16_f32 v206, v206, v207
	v_cvt_pk_bf16_f32 v207, v208, v209
	global_store_dwordx2 v[184:185], v[206:207], off offset:64
	v_mul_f32_e32 v210, v191, v210
	v_mul_f32_e32 v211, v191, v211
	v_mul_f32_e32 v212, v191, v212
	v_mul_f32_e32 v213, v191, v213
	v_cvt_pk_bf16_f32 v210, v210, v211
	v_cvt_pk_bf16_f32 v211, v212, v213
	global_store_dwordx2 v[184:185], v[210:211], off offset:96
	s_barrier
	ds_read_b128 v[104:107], v178 offset:49152
	ds_read_b128 v[146:149], v178 offset:57344
	ds_read_b128 v[108:111], v178 offset:50176
	ds_read_b128 v[150:153], v178 offset:58368
	ds_read_b128 v[112:115], v178 offset:51200
	ds_read_b128 v[154:157], v178 offset:59392
	ds_read_b128 v[116:119], v178 offset:52224
	ds_read_b128 v[158:161], v178 offset:60416
	ds_read_b128 v[120:123], v178 offset:53248
	ds_read_b128 v[162:165], v178 offset:61440
	ds_read_b128 v[124:127], v178 offset:54272
	ds_read_b128 v[166:169], v178 offset:62464
	ds_read_b128 v[128:131], v178 offset:55296
	ds_read_b128 v[170:173], v178 offset:63488
	ds_read_b128 v[132:135], v178 offset:56320
	ds_read_b128 v[174:177], v178 offset:64512
	s_waitcnt lgkmcnt(0)
	s_waitcnt vmcnt(10)
	s_barrier
	v_mfma_f32_16x16x32_bf16 v[206:209], v[104:107], v[32:35], 0
	v_mfma_f32_16x16x32_bf16 v[210:213], v[146:149], v[32:35], 0
	v_mfma_f32_16x16x32_bf16 v[206:209], v[108:111], v[40:43], v[206:209]
	v_mfma_f32_16x16x32_bf16 v[210:213], v[150:153], v[40:43], v[210:213]
	v_mfma_f32_16x16x32_bf16 v[206:209], v[112:115], v[48:51], v[206:209]
	v_mfma_f32_16x16x32_bf16 v[210:213], v[154:157], v[48:51], v[210:213]
	v_mfma_f32_16x16x32_bf16 v[206:209], v[116:119], v[56:59], v[206:209]
	v_mfma_f32_16x16x32_bf16 v[210:213], v[158:161], v[56:59], v[210:213]
	v_mfma_f32_16x16x32_bf16 v[206:209], v[120:123], v[72:75], v[206:209]
	v_mfma_f32_16x16x32_bf16 v[210:213], v[162:165], v[72:75], v[210:213]
	v_mfma_f32_16x16x32_bf16 v[206:209], v[124:127], v[80:83], v[206:209]
	v_mfma_f32_16x16x32_bf16 v[210:213], v[166:169], v[80:83], v[210:213]
	v_mfma_f32_16x16x32_bf16 v[206:209], v[128:131], v[88:91], v[206:209]
	v_mfma_f32_16x16x32_bf16 v[210:213], v[170:173], v[88:91], v[210:213]
	v_mfma_f32_16x16x32_bf16 v[206:209], v[132:135], v[96:99], v[206:209]
	v_mfma_f32_16x16x32_bf16 v[210:213], v[174:177], v[96:99], v[210:213]
	v_mul_f32_e32 v192, v191, v192
	v_mul_f32_e32 v193, v191, v193
	v_mul_f32_e32 v194, v191, v194
	v_mul_f32_e32 v195, v191, v195
	v_cvt_pk_bf16_f32 v192, v192, v193
	v_cvt_pk_bf16_f32 v193, v194, v195
	global_store_dwordx2 v[184:185], v[192:193], off offset:128
	v_mul_f32_e32 v196, v191, v196
	v_mul_f32_e32 v197, v191, v197
	v_mul_f32_e32 v198, v191, v198
	v_mul_f32_e32 v199, v191, v199
	v_cvt_pk_bf16_f32 v196, v196, v197
	v_cvt_pk_bf16_f32 v197, v198, v199
	global_store_dwordx2 v[184:185], v[196:197], off offset:160
	s_barrier
; __device__ __forceinline__ unsigned cvt_pk_bf16(float lo, float hi) { unsigned r; asm volatile("v_cvt_pk_bf16_f32 %0, %1, %2" : "=v"(r) : "v"(lo), "v"(hi)); return r; }
; __device__ __forceinline__ f32x4 mfma16(bf16x8 a, bf16x8 b, f32x4 c) { return __builtin_amdgcn_mfma_f32_16x16x32_bf16(a, b, c, 0, 0, 0); }
; __device__ __forceinline__ void mem_task(bf16_t* zb, const bf16_t* kvm_b, const bf16_t* vmt_b, int hm, int t0, int lane, bool do_store) {
;     ...
; #pragma unroll
;     for (int dt = 0; dt < 16; ++dt) {
;         if (dt + 2 < 16) { const bf16_t* vp = vbase + (size_t)((dt + 2) * 16) * 256;
; #pragma unroll
;             for (int kp = 0; kp < 8; ++kp) vfr[(dt + 2) % 3][kp] = *(const bf16x8*)(vp + kp * 32); }
;         f32x4 acc = zero4;
;         __builtin_amdgcn_s_setprio(1);
; #pragma unroll
;         for (int kp = 0; kp < 8; ++kp) acc = mfma16(vfr[dt % 3][kp], pf[kp], acc);
;         __builtin_amdgcn_s_setprio(0);
;         u32x2 w; w.x = cvt_pk_bf16(acc[0] * il, acc[1] * il); w.y = cvt_pk_bf16(acc[2] * il, acc[3] * il); if (do_store || acc[0] == 12345.678f) *(u32x2*)(qp + dt * 16 + 4 * fq) = w; }
	ds_read_b128 v[104:107], v179 offset:0
	ds_read_b128 v[146:149], v179 offset:8192
	ds_read_b128 v[108:111], v179 offset:1024
	ds_read_b128 v[150:153], v179 offset:9216
	ds_read_b128 v[112:115], v179 offset:2048
	ds_read_b128 v[154:157], v179 offset:10240
	ds_read_b128 v[116:119], v179 offset:3072
	ds_read_b128 v[158:161], v179 offset:11264
	ds_read_b128 v[120:123], v179 offset:4096
	ds_read_b128 v[162:165], v179 offset:12288
	ds_read_b128 v[124:127], v179 offset:5120
	ds_read_b128 v[166:169], v179 offset:13312
	ds_read_b128 v[128:131], v179 offset:6144
	ds_read_b128 v[170:173], v179 offset:14336
	ds_read_b128 v[132:135], v179 offset:7168
	ds_read_b128 v[174:177], v179 offset:15360
	s_waitcnt lgkmcnt(0)
	s_waitcnt vmcnt(10)
	s_barrier
	v_mfma_f32_16x16x32_bf16 v[192:195], v[104:107], v[32:35], 0
	v_mfma_f32_16x16x32_bf16 v[196:199], v[146:149], v[32:35], 0
	v_mfma_f32_16x16x32_bf16 v[192:195], v[108:111], v[40:43], v[192:195]
	v_mfma_f32_16x16x32_bf16 v[196:199], v[150:153], v[40:43], v[196:199]
	v_mfma_f32_16x16x32_bf16 v[192:195], v[112:115], v[48:51], v[192:195]
	v_mfma_f32_16x16x32_bf16 v[196:199], v[154:157], v[48:51], v[196:199]
	v_mfma_f32_16x16x32_bf16 v[192:195], v[116:119], v[56:59], v[192:195]
	v_mfma_f32_16x16x32_bf16 v[196:199], v[158:161], v[56:59], v[196:199]
	v_mfma_f32_16x16x32_bf16 v[192:195], v[120:123], v[72:75], v[192:195]
	v_mfma_f32_16x16x32_bf16 v[196:199], v[162:165], v[72:75], v[196:199]
	v_mfma_f32_16x16x32_bf16 v[192:195], v[124:127], v[80:83], v[192:195]
	v_mfma_f32_16x16x32_bf16 v[196:199], v[166:169], v[80:83], v[196:199]
	v_mfma_f32_16x16x32_bf16 v[192:195], v[128:131], v[88:91], v[192:195]
	v_mfma_f32_16x16x32_bf16 v[196:199], v[170:173], v[88:91], v[196:199]
	v_mfma_f32_16x16x32_bf16 v[192:195], v[132:135], v[96:99], v[192:195]
	v_mfma_f32_16x16x32_bf16 v[196:199], v[174:177], v[96:99], v[196:199]
	v_mul_f32_e32 v206, v191, v206
	v_mul_f32_e32 v207, v191, v207
	v_mul_f32_e32 v208, v191, v208
	v_mul_f32_e32 v209, v191, v209
	v_cvt_pk_bf16_f32 v206, v206, v207
	v_cvt_pk_bf16_f32 v207, v208, v209
	global_store_dwordx2 v[184:185], v[206:207], off offset:192
	v_mul_f32_e32 v210, v191, v210
	v_mul_f32_e32 v211, v191, v211
	v_mul_f32_e32 v212, v191, v212
	v_mul_f32_e32 v213, v191, v213
	v_cvt_pk_bf16_f32 v210, v210, v211
	v_cvt_pk_bf16_f32 v211, v212, v213
	global_store_dwordx2 v[184:185], v[210:211], off offset:224
	s_barrier
	ds_read_b128 v[104:107], v179 offset:16384
	ds_read_b128 v[146:149], v179 offset:24576
	ds_read_b128 v[108:111], v179 offset:17408
	ds_read_b128 v[150:153], v179 offset:25600
	ds_read_b128 v[112:115], v179 offset:18432
	ds_read_b128 v[154:157], v179 offset:26624
	ds_read_b128 v[116:119], v179 offset:19456
	ds_read_b128 v[158:161], v179 offset:27648
	ds_read_b128 v[120:123], v179 offset:20480
	ds_read_b128 v[162:165], v179 offset:28672
	ds_read_b128 v[124:127], v179 offset:21504
	ds_read_b128 v[166:169], v179 offset:29696
	ds_read_b128 v[128:131], v179 offset:22528
	ds_read_b128 v[170:173], v179 offset:30720
	ds_read_b128 v[132:135], v179 offset:23552
	ds_read_b128 v[174:177], v179 offset:31744
	s_waitcnt lgkmcnt(0)
	s_waitcnt vmcnt(10)
	s_barrier
	v_mfma_f32_16x16x32_bf16 v[206:209], v[104:107], v[32:35], 0
	v_mfma_f32_16x16x32_bf16 v[210:213], v[146:149], v[32:35], 0
	v_mfma_f32_16x16x32_bf16 v[206:209], v[108:111], v[40:43], v[206:209]
	v_mfma_f32_16x16x32_bf16 v[210:213], v[150:153], v[40:43], v[210:213]
	v_mfma_f32_16x16x32_bf16 v[206:209], v[112:115], v[48:51], v[206:209]
	v_mfma_f32_16x16x32_bf16 v[210:213], v[154:157], v[48:51], v[210:213]
	v_mfma_f32_16x16x32_bf16 v[206:209], v[116:119], v[56:59], v[206:209]
	v_mfma_f32_16x16x32_bf16 v[210:213], v[158:161], v[56:59], v[210:213]
	v_mfma_f32_16x16x32_bf16 v[206:209], v[120:123], v[72:75], v[206:209]
	v_mfma_f32_16x16x32_bf16 v[210:213], v[162:165], v[72:75], v[210:213]
	v_mfma_f32_16x16x32_bf16 v[206:209], v[124:127], v[80:83], v[206:209]
	v_mfma_f32_16x16x32_bf16 v[210:213], v[166:169], v[80:83], v[210:213]
	v_mfma_f32_16x16x32_bf16 v[206:209], v[128:131], v[88:91], v[206:209]
	v_mfma_f32_16x16x32_bf16 v[210:213], v[170:173], v[88:91], v[210:213]
	v_mfma_f32_16x16x32_bf16 v[206:209], v[132:135], v[96:99], v[206:209]
	v_mfma_f32_16x16x32_bf16 v[210:213], v[174:177], v[96:99], v[210:213]
	v_mul_f32_e32 v192, v191, v192
	v_mul_f32_e32 v193, v191, v193
	v_mul_f32_e32 v194, v191, v194
	v_mul_f32_e32 v195, v191, v195
	v_cvt_pk_bf16_f32 v192, v192, v193
	v_cvt_pk_bf16_f32 v193, v194, v195
	global_store_dwordx2 v[184:185], v[192:193], off offset:256
	v_mul_f32_e32 v196, v191, v196
	v_mul_f32_e32 v197, v191, v197
	v_mul_f32_e32 v198, v191, v198
	v_mul_f32_e32 v199, v191, v199
	v_cvt_pk_bf16_f32 v196, v196, v197
	v_cvt_pk_bf16_f32 v197, v198, v199
	global_store_dwordx2 v[184:185], v[196:197], off offset:288
	s_barrier
; __device__ __forceinline__ unsigned cvt_pk_bf16(float lo, float hi) { unsigned r; asm volatile("v_cvt_pk_bf16_f32 %0, %1, %2" : "=v"(r) : "v"(lo), "v"(hi)); return r; }
; __device__ __forceinline__ f32x4 mfma16(bf16x8 a, bf16x8 b, f32x4 c) { return __builtin_amdgcn_mfma_f32_16x16x32_bf16(a, b, c, 0, 0, 0); }
; __device__ __forceinline__ void mem_task(bf16_t* zb, const bf16_t* kvm_b, const bf16_t* vmt_b, int hm, int t0, int lane, bool do_store) {
;     ...
; #pragma unroll
;     for (int dt = 0; dt < 16; ++dt) {
;         if (dt + 2 < 16) { const bf16_t* vp = vbase + (size_t)((dt + 2) * 16) * 256;
; #pragma unroll
;             for (int kp = 0; kp < 8; ++kp) vfr[(dt + 2) % 3][kp] = *(const bf16x8*)(vp + kp * 32); }
;         f32x4 acc = zero4;
;         __builtin_amdgcn_s_setprio(1);
; #pragma unroll
;         for (int kp = 0; kp < 8; ++kp) acc = mfma16(vfr[dt % 3][kp], pf[kp], acc);
;         __builtin_amdgcn_s_setprio(0);
;         u32x2 w; w.x = cvt_pk_bf16(acc[0] * il, acc[1] * il); w.y = cvt_pk_bf16(acc[2] * il, acc[3] * il); if (do_store || acc[0] == 12345.678f) *(u32x2*)(qp + dt * 16 + 4 * fq) = w; }
; __global__ void __launch_bounds__(512, 2) mega(Args a) {
;     ...
;             for (int prep_ = 0; prep_ < PROBE_C2; ++prep_) for (int it = gw; it < (SEQ / 16) * 4; it += NGW) { const int hm = it & 3, t0 = (it >> 2) * 16;
;                 mem_task(ZMAIN, KVM + (size_t)b * 256 * 2048, VMT + (size_t)b * 4 * 256 * 256, hm, t0, lane, prep_ == PROBE_C2 - 1); }
	ds_read_b128 v[104:107], v179 offset:32768
	ds_read_b128 v[146:149], v179 offset:40960
	ds_read_b128 v[108:111], v179 offset:33792
	ds_read_b128 v[150:153], v179 offset:41984
	ds_read_b128 v[112:115], v179 offset:34816
	ds_read_b128 v[154:157], v179 offset:43008
	ds_read_b128 v[116:119], v179 offset:35840
	ds_read_b128 v[158:161], v179 offset:44032
	ds_read_b128 v[120:123], v179 offset:36864
	ds_read_b128 v[162:165], v179 offset:45056
	ds_read_b128 v[124:127], v179 offset:37888
	ds_read_b128 v[166:169], v179 offset:46080
	ds_read_b128 v[128:131], v179 offset:38912
	ds_read_b128 v[170:173], v179 offset:47104
	ds_read_b128 v[132:135], v179 offset:39936
	ds_read_b128 v[174:177], v179 offset:48128
	s_waitcnt lgkmcnt(0)
	s_waitcnt vmcnt(10)
	s_barrier
	v_mfma_f32_16x16x32_bf16 v[192:195], v[104:107], v[32:35], 0
	v_mfma_f32_16x16x32_bf16 v[196:199], v[146:149], v[32:35], 0
	v_mfma_f32_16x16x32_bf16 v[192:195], v[108:111], v[40:43], v[192:195]
	v_mfma_f32_16x16x32_bf16 v[196:199], v[150:153], v[40:43], v[196:199]
	v_mfma_f32_16x16x32_bf16 v[192:195], v[112:115], v[48:51], v[192:195]
	v_mfma_f32_16x16x32_bf16 v[196:199], v[154:157], v[48:51], v[196:199]
	v_mfma_f32_16x16x32_bf16 v[192:195], v[116:119], v[56:59], v[192:195]
	v_mfma_f32_16x16x32_bf16 v[196:199], v[158:161], v[56:59], v[196:199]
	v_mfma_f32_16x16x32_bf16 v[192:195], v[120:123], v[72:75], v[192:195]
	v_mfma_f32_16x16x32_bf16 v[196:199], v[162:165], v[72:75], v[196:199]
	v_mfma_f32_16x16x32_bf16 v[192:195], v[124:127], v[80:83], v[192:195]
	v_mfma_f32_16x16x32_bf16 v[196:199], v[166:169], v[80:83], v[196:199]
	v_mfma_f32_16x16x32_bf16 v[192:195], v[128:131], v[88:91], v[192:195]
	v_mfma_f32_16x16x32_bf16 v[196:199], v[170:173], v[88:91], v[196:199]
	v_mfma_f32_16x16x32_bf16 v[192:195], v[132:135], v[96:99], v[192:195]
	v_mfma_f32_16x16x32_bf16 v[196:199], v[174:177], v[96:99], v[196:199]
	v_mul_f32_e32 v206, v191, v206
	v_mul_f32_e32 v207, v191, v207
	v_mul_f32_e32 v208, v191, v208
	v_mul_f32_e32 v209, v191, v209
	v_cvt_pk_bf16_f32 v206, v206, v207
	v_cvt_pk_bf16_f32 v207, v208, v209
	global_store_dwordx2 v[184:185], v[206:207], off offset:320
	v_mul_f32_e32 v210, v191, v210
	v_mul_f32_e32 v211, v191, v211
	v_mul_f32_e32 v212, v191, v212
	v_mul_f32_e32 v213, v191, v213
	v_cvt_pk_bf16_f32 v210, v210, v211
	v_cvt_pk_bf16_f32 v211, v212, v213
	global_store_dwordx2 v[184:185], v[210:211], off offset:352
	s_barrier
	ds_read_b128 v[104:107], v179 offset:49152
	ds_read_b128 v[146:149], v179 offset:57344
	ds_read_b128 v[108:111], v179 offset:50176
	ds_read_b128 v[150:153], v179 offset:58368
	ds_read_b128 v[112:115], v179 offset:51200
	ds_read_b128 v[154:157], v179 offset:59392
	ds_read_b128 v[116:119], v179 offset:52224
	ds_read_b128 v[158:161], v179 offset:60416
	ds_read_b128 v[120:123], v179 offset:53248
	ds_read_b128 v[162:165], v179 offset:61440
	ds_read_b128 v[124:127], v179 offset:54272
	ds_read_b128 v[166:169], v179 offset:62464
	ds_read_b128 v[128:131], v179 offset:55296
	ds_read_b128 v[170:173], v179 offset:63488
	ds_read_b128 v[132:135], v179 offset:56320
	ds_read_b128 v[174:177], v179 offset:64512
	s_waitcnt lgkmcnt(0)
	s_barrier
	v_mfma_f32_16x16x32_bf16 v[206:209], v[104:107], v[32:35], 0
	v_mfma_f32_16x16x32_bf16 v[210:213], v[146:149], v[32:35], 0
	v_mfma_f32_16x16x32_bf16 v[206:209], v[108:111], v[40:43], v[206:209]
	v_mfma_f32_16x16x32_bf16 v[210:213], v[150:153], v[40:43], v[210:213]
	v_mfma_f32_16x16x32_bf16 v[206:209], v[112:115], v[48:51], v[206:209]
	v_mfma_f32_16x16x32_bf16 v[210:213], v[154:157], v[48:51], v[210:213]
	v_mfma_f32_16x16x32_bf16 v[206:209], v[116:119], v[56:59], v[206:209]
	v_mfma_f32_16x16x32_bf16 v[210:213], v[158:161], v[56:59], v[210:213]
	v_mfma_f32_16x16x32_bf16 v[206:209], v[120:123], v[72:75], v[206:209]
	v_mfma_f32_16x16x32_bf16 v[210:213], v[162:165], v[72:75], v[210:213]
	v_mfma_f32_16x16x32_bf16 v[206:209], v[124:127], v[80:83], v[206:209]
	v_mfma_f32_16x16x32_bf16 v[210:213], v[166:169], v[80:83], v[210:213]
	v_mfma_f32_16x16x32_bf16 v[206:209], v[128:131], v[88:91], v[206:209]
	v_mfma_f32_16x16x32_bf16 v[210:213], v[170:173], v[88:91], v[210:213]
	v_mfma_f32_16x16x32_bf16 v[206:209], v[132:135], v[96:99], v[206:209]
	v_mfma_f32_16x16x32_bf16 v[210:213], v[174:177], v[96:99], v[210:213]
	v_mul_f32_e32 v192, v191, v192
	v_mul_f32_e32 v193, v191, v193
	v_mul_f32_e32 v194, v191, v194
	v_mul_f32_e32 v195, v191, v195
	v_cvt_pk_bf16_f32 v192, v192, v193
	v_cvt_pk_bf16_f32 v193, v194, v195
	global_store_dwordx2 v[184:185], v[192:193], off offset:384
	v_mul_f32_e32 v196, v191, v196
	v_mul_f32_e32 v197, v191, v197
	v_mul_f32_e32 v198, v191, v198
	v_mul_f32_e32 v199, v191, v199
	v_cvt_pk_bf16_f32 v196, v196, v197
	v_cvt_pk_bf16_f32 v197, v198, v199
	global_store_dwordx2 v[184:185], v[196:197], off offset:416
	s_cmp_lt_u32 s89, 4
	s_cbranch_scc0 .Lmem_r_trail1
	s_barrier
.Lmem_r_trail1:
	s_nop 7
	s_nop 7
	v_mul_f32_e32 v206, v191, v206
	v_mul_f32_e32 v207, v191, v207
	v_mul_f32_e32 v208, v191, v208
	v_mul_f32_e32 v209, v191, v209
	v_cvt_pk_bf16_f32 v206, v206, v207
	v_cvt_pk_bf16_f32 v207, v208, v209
	global_store_dwordx2 v[184:185], v[206:207], off offset:448
	v_mul_f32_e32 v210, v191, v210
	v_mul_f32_e32 v211, v191, v211
	v_mul_f32_e32 v212, v191, v212
	v_mul_f32_e32 v213, v191, v213
	v_cvt_pk_bf16_f32 v210, v210, v211
	v_cvt_pk_bf16_f32 v211, v212, v213
	global_store_dwordx2 v[184:185], v[210:211], off offset:480
	s_add_i32 s5, s5, s64
	s_cmpk_gt_i32 s5, 0x7ff
	s_cbranch_scc0 .LBB0_366
